# w_out/w_down store epilogue software-pipelined: next block's cvt_pk fills the permlane16_swap wait states (s_nop removed), stores issue earlier; on top of v47
# speedup vs baseline: 1.0066x; 1.0066x over previous
.Lg160o_epi:
	s_mulk_i32 s15, 0xa0
	v_or_b32_e32 v90, s15, v96
	s_mov_b32 s9, s45
	v_ashrrev_i32_e32 v91, 31, v90
	v_lshl_add_u64 v[92:93], v[84:85], 0, s[8:9]
	v_lshlrev_b64 v[94:95], 10, v[90:91]
	v_lshl_add_u64 v[94:95], v[94:95], 0, v[92:93]
	s_barrier
	v_lshl_add_u64 v[94:95], v[94:95], 1, s[6:7]
	v_bfe_u32 v90, v222, 4, 1
	v_mul_u32_u24_e32 v90, 24, v90
	v_mov_b32_e32 v91, 0
	v_lshl_add_u64 v[94:95], v[90:91], 0, v[94:95]
	s_mov_b64 s[12:13], 0x8000
	v_cvt_pk_bf16_f32 v76, v76, v77
	v_cvt_pk_bf16_f32 v77, v78, v79
	v_cvt_pk_bf16_f32 v78, v72, v73
	v_cvt_pk_bf16_f32 v79, v74, v75
	v_cvt_pk_bf16_f32 v68, v68, v69
	v_cvt_pk_bf16_f32 v69, v70, v71
	v_cvt_pk_bf16_f32 v70, v64, v65
	v_cvt_pk_bf16_f32 v71, v66, v67
	v_permlane16_swap_b32_e32 v76, v78
	v_permlane16_swap_b32_e32 v77, v79
	flat_store_dwordx4 v[94:95], v[76:79]
	v_lshl_add_u64 v[94:95], v[94:95], 0, s[12:13]
	v_cvt_pk_bf16_f32 v60, v60, v61
	v_cvt_pk_bf16_f32 v61, v62, v63
	v_cvt_pk_bf16_f32 v62, v56, v57
	v_cvt_pk_bf16_f32 v63, v58, v59
	v_permlane16_swap_b32_e32 v68, v70
	v_permlane16_swap_b32_e32 v69, v71
	flat_store_dwordx4 v[94:95], v[68:71]
	v_lshl_add_u64 v[94:95], v[94:95], 0, s[12:13]
	v_cvt_pk_bf16_f32 v52, v52, v53
	v_cvt_pk_bf16_f32 v53, v54, v55
	v_cvt_pk_bf16_f32 v54, v48, v49
	v_cvt_pk_bf16_f32 v55, v50, v51
	v_permlane16_swap_b32_e32 v60, v62
	v_permlane16_swap_b32_e32 v61, v63
	flat_store_dwordx4 v[94:95], v[60:63]
	v_lshl_add_u64 v[94:95], v[94:95], 0, s[12:13]
	v_cvt_pk_bf16_f32 v44, v44, v45
	v_cvt_pk_bf16_f32 v45, v46, v47
	v_cvt_pk_bf16_f32 v46, v40, v41
	v_cvt_pk_bf16_f32 v47, v42, v43
	v_permlane16_swap_b32_e32 v52, v54
	v_permlane16_swap_b32_e32 v53, v55
	flat_store_dwordx4 v[94:95], v[52:55]
	v_lshl_add_u64 v[94:95], v[94:95], 0, s[12:13]
	v_cvt_pk_bf16_f32 v36, v36, v37
	v_cvt_pk_bf16_f32 v37, v38, v39
	v_cvt_pk_bf16_f32 v38, v32, v33
	v_cvt_pk_bf16_f32 v39, v34, v35
	v_permlane16_swap_b32_e32 v44, v46
	v_permlane16_swap_b32_e32 v45, v47
	flat_store_dwordx4 v[94:95], v[44:47]
	v_lshl_add_u64 v[94:95], v[94:95], 0, s[12:13]
	v_cvt_pk_bf16_f32 v28, v28, v29
	v_cvt_pk_bf16_f32 v29, v30, v31
	v_cvt_pk_bf16_f32 v30, v24, v25
	v_cvt_pk_bf16_f32 v31, v26, v27
	v_permlane16_swap_b32_e32 v36, v38
	v_permlane16_swap_b32_e32 v37, v39
	flat_store_dwordx4 v[94:95], v[36:39]
	v_lshl_add_u64 v[94:95], v[94:95], 0, s[12:13]
	v_cvt_pk_bf16_f32 v20, v20, v21
	v_cvt_pk_bf16_f32 v21, v22, v23
	v_cvt_pk_bf16_f32 v22, v16, v17
	v_cvt_pk_bf16_f32 v23, v18, v19
	v_permlane16_swap_b32_e32 v28, v30
	v_permlane16_swap_b32_e32 v29, v31
	flat_store_dwordx4 v[94:95], v[28:31]
	v_lshl_add_u64 v[94:95], v[94:95], 0, s[12:13]
	v_cvt_pk_bf16_f32 v12, v12, v13
	v_cvt_pk_bf16_f32 v13, v14, v15
	v_cvt_pk_bf16_f32 v14, v8, v9
	v_cvt_pk_bf16_f32 v15, v10, v11
	v_permlane16_swap_b32_e32 v20, v22
	v_permlane16_swap_b32_e32 v21, v23
	flat_store_dwordx4 v[94:95], v[20:23]
	v_lshl_add_u64 v[94:95], v[94:95], 0, s[12:13]
	v_cvt_pk_bf16_f32 v4, v4, v5
	v_cvt_pk_bf16_f32 v5, v6, v7
	v_cvt_pk_bf16_f32 v6, v0, v1
	v_cvt_pk_bf16_f32 v7, v2, v3
	v_permlane16_swap_b32_e32 v12, v14
	v_permlane16_swap_b32_e32 v13, v15
	flat_store_dwordx4 v[94:95], v[12:15]
	v_lshl_add_u64 v[94:95], v[94:95], 0, s[12:13]
	s_nop 1
	v_permlane16_swap_b32_e32 v4, v6
	v_permlane16_swap_b32_e32 v5, v7
	flat_store_dwordx4 v[94:95], v[4:7]
	s_add_i32 s14, s14, 1
	s_mov_b32 s100, s101
	s_mov_b64 s[8:9], 0
